# outproj: all 32 k-steps in the ring loop, residual add with 12 loads in flight and counted waits (replaces the one-load-per-vmcnt(0) ladder)
# baseline (speedup 1.0000x reference)
; #define BLOADG(kt) do { \
;     _Pragma("unroll") for (int i = 0; i < 2; ++i) ra[i] = *(const u32x4*)(ap + (size_t)(64 * i) * lda + (kt) * 32); \
;     _Pragma("unroll") for (int i = 0; i < 4; ++i) rb[i] = *(const u32x4*)(bp + (size_t)((i & 1) * s1 + (i >> 1) * s2) * ldb + (kt) * 32); } while (0)
; #define BSTOREG(st) do { \
;     _Pragma("unroll") for (int i = 0; i < 2; ++i) *(u32x4*)(sA + (st) * BGA + so + 64 * i * 32) = ra[i]; \
;     _Pragma("unroll") for (int i = 0; i < 4; ++i) *(u32x4*)(sB + (st) * BGB + so + 64 * i * 32) = rb[i]; } while (0)
;     ...
;   for (int kt = 0; kt < nk; ++kt) {
;     const int cur = kt & 1;
;     if (kt + 1 < nk) { BSTOREG(cur ^ 1); if (kt + 2 < nk) BLOADG(kt + 2); }
;     const bf16_t* cA = sA + cur * BGA + (wm * 64) * 32 + fo; const bf16_t* cB = sB + cur * BGB + (wn * 128) * 32 + fo;
;     bf16x8 af[4];
; #pragma unroll
;     for (int mi = 0; mi < 4; ++mi) af[mi] = *(const bf16x8*)(cA + mi * 16 * 32);
; #pragma unroll
;     for (int nh = 0; nh < 2; ++nh) {
;       bf16x8 bfr[4];
; #pragma unroll
;       for (int ni = 0; ni < 4; ++ni) bfr[ni] = *(const bf16x8*)(cB + (nh * 4 + ni) * 16 * 32);
; #pragma unroll
;       for (int mi = 0; mi < 4; ++mi)
; #pragma unroll
;         for (int ni = 0; ni < 4; ++ni) acc[mi][nh * 4 + ni] = __builtin_amdgcn_mfma_f32_16x16x32_bf16(bfr[ni], af[mi], acc[mi][nh * 4 + ni], 0, 0, 0);
;     }
;     __syncthreads();
.LBB0_238:
	ds_read_b128 v[166:169], v163 offset:0
	ds_read_b128 v[170:173], v163 offset:1024
	ds_read_b128 v[174:177], v163 offset:2048
	ds_read_b128 v[178:181], v163 offset:3072
	ds_read_b128 v[182:185], v162 offset:16384
	ds_read_b128 v[206:209], v162 offset:17408
	ds_read_b128 v[210:213], v162 offset:18432
	ds_read_b128 v[214:217], v162 offset:19456
	s_waitcnt lgkmcnt(7)
	s_waitcnt lgkmcnt(3)
	v_mfma_f32_16x16x32_bf16 v[150:153], v[182:185], v[166:169], v[150:153]
	v_mfma_f32_16x16x32_bf16 v[134:137], v[182:185], v[170:173], v[134:137]
	v_mfma_f32_16x16x32_bf16 v[98:101], v[182:185], v[174:177], v[98:101]
	v_mfma_f32_16x16x32_bf16 v[66:69], v[182:185], v[178:181], v[66:69]
	ds_read_b128 v[182:185], v162 offset:20480
	s_add_u32 m0, m0, 0x9400
	s_nop 0
	global_load_lds_dwordx4 v218, s[26:27]
	global_load_dwordx4 v[118:121], v218, s[26:27] offset:64
	s_waitcnt lgkmcnt(3)
	v_mfma_f32_16x16x32_bf16 v[146:149], v[206:209], v[166:169], v[146:149]
	v_mfma_f32_16x16x32_bf16 v[130:133], v[206:209], v[170:173], v[130:133]
	v_mfma_f32_16x16x32_bf16 v[86:89], v[206:209], v[174:177], v[86:89]
	v_mfma_f32_16x16x32_bf16 v[62:65], v[206:209], v[178:181], v[62:65]
	ds_read_b128 v[206:209], v162 offset:21504
	s_add_u32 m0, m0, 0x1000
	s_nop 0
	global_load_lds_dwordx4 v219, s[26:27]
	global_load_dwordx4 v[114:117], v219, s[26:27] offset:64
	s_waitcnt lgkmcnt(3)
	v_mfma_f32_16x16x32_bf16 v[142:145], v[210:213], v[166:169], v[142:145]
	v_mfma_f32_16x16x32_bf16 v[126:129], v[210:213], v[170:173], v[126:129]
	v_mfma_f32_16x16x32_bf16 v[78:81], v[210:213], v[174:177], v[78:81]
	v_mfma_f32_16x16x32_bf16 v[54:57], v[210:213], v[178:181], v[54:57]
	ds_read_b128 v[210:213], v162 offset:22528
	s_sub_u32 m0, m0, 0x5400
	s_nop 0
	global_load_lds_dwordx4 v220, s[28:29]
	global_load_dwordx4 v[110:113], v220, s[28:29] offset:64
	s_waitcnt lgkmcnt(3)
	v_mfma_f32_16x16x32_bf16 v[138:141], v[214:217], v[166:169], v[138:141]
	v_mfma_f32_16x16x32_bf16 v[122:125], v[214:217], v[170:173], v[122:125]
	v_mfma_f32_16x16x32_bf16 v[74:77], v[214:217], v[174:177], v[74:77]
	v_mfma_f32_16x16x32_bf16 v[50:53], v[214:217], v[178:181], v[50:53]
	ds_read_b128 v[214:217], v162 offset:23552
	s_add_u32 m0, m0, 0x1000
	s_nop 0
	global_load_lds_dwordx4 v221, s[28:29]
	global_load_dwordx4 v[106:109], v221, s[28:29] offset:64
	s_waitcnt lgkmcnt(3)
	v_mfma_f32_16x16x32_bf16 v[102:105], v[182:185], v[166:169], v[102:105]
	v_mfma_f32_16x16x32_bf16 v[46:49], v[182:185], v[170:173], v[46:49]
	v_mfma_f32_16x16x32_bf16 v[30:33], v[182:185], v[174:177], v[30:33]
	v_mfma_f32_16x16x32_bf16 v[14:17], v[182:185], v[178:181], v[14:17]
	s_add_u32 m0, m0, 0x1000
	s_nop 0
	global_load_lds_dwordx4 v190, s[28:29]
	global_load_dwordx4 v[90:93], v190, s[28:29] offset:64
	s_waitcnt lgkmcnt(2)
	v_mfma_f32_16x16x32_bf16 v[82:85], v[206:209], v[166:169], v[82:85]
	v_mfma_f32_16x16x32_bf16 v[42:45], v[206:209], v[170:173], v[42:45]
	v_mfma_f32_16x16x32_bf16 v[26:29], v[206:209], v[174:177], v[26:29]
	v_mfma_f32_16x16x32_bf16 v[10:13], v[206:209], v[178:181], v[10:13]
	s_add_u32 m0, m0, 0x1000
	s_nop 0
	global_load_lds_dwordx4 v191, s[28:29]
	global_load_dwordx4 v[94:97], v191, s[28:29] offset:64
	s_add_u32 s26, s26, 0x80
	s_addc_u32 s27, s27, 0
	s_add_u32 s28, s28, 0x80
	s_addc_u32 s29, s29, 0
	s_waitcnt lgkmcnt(1)
	v_mfma_f32_16x16x32_bf16 v[70:73], v[210:213], v[166:169], v[70:73]
	v_mfma_f32_16x16x32_bf16 v[38:41], v[210:213], v[170:173], v[38:41]
	v_mfma_f32_16x16x32_bf16 v[22:25], v[210:213], v[174:177], v[22:25]
	v_mfma_f32_16x16x32_bf16 v[6:9], v[210:213], v[178:181], v[6:9]
	s_waitcnt lgkmcnt(0)
	s_barrier
	v_mfma_f32_16x16x32_bf16 v[58:61], v[214:217], v[166:169], v[58:61]
	v_mfma_f32_16x16x32_bf16 v[34:37], v[214:217], v[170:173], v[34:37]
	v_mfma_f32_16x16x32_bf16 v[18:21], v[214:217], v[174:177], v[18:21]
	v_mfma_f32_16x16x32_bf16 v[2:5], v[214:217], v[178:181], v[2:5]
	ds_read_b128 v[166:169], v163 offset:8192
	ds_read_b128 v[170:173], v163 offset:9216
	ds_read_b128 v[174:177], v163 offset:10240
	ds_read_b128 v[178:181], v163 offset:11264
	ds_read_b128 v[182:185], v162 offset:32768
	ds_read_b128 v[206:209], v162 offset:33792
	ds_read_b128 v[210:213], v162 offset:34816
	ds_read_b128 v[214:217], v162 offset:35840
	s_waitcnt lgkmcnt(7)
	s_waitcnt lgkmcnt(3)
	v_mfma_f32_16x16x32_bf16 v[150:153], v[182:185], v[166:169], v[150:153]
	v_mfma_f32_16x16x32_bf16 v[134:137], v[182:185], v[170:173], v[134:137]
	v_mfma_f32_16x16x32_bf16 v[98:101], v[182:185], v[174:177], v[98:101]
	v_mfma_f32_16x16x32_bf16 v[66:69], v[182:185], v[178:181], v[66:69]
	ds_read_b128 v[182:185], v162 offset:36864
	s_waitcnt lgkmcnt(3)
	v_mfma_f32_16x16x32_bf16 v[146:149], v[206:209], v[166:169], v[146:149]
	v_mfma_f32_16x16x32_bf16 v[130:133], v[206:209], v[170:173], v[130:133]
	v_mfma_f32_16x16x32_bf16 v[86:89], v[206:209], v[174:177], v[86:89]
	v_mfma_f32_16x16x32_bf16 v[62:65], v[206:209], v[178:181], v[62:65]
	ds_read_b128 v[206:209], v162 offset:37888
	s_waitcnt lgkmcnt(3)
	v_mfma_f32_16x16x32_bf16 v[142:145], v[210:213], v[166:169], v[142:145]
	v_mfma_f32_16x16x32_bf16 v[126:129], v[210:213], v[170:173], v[126:129]
	v_mfma_f32_16x16x32_bf16 v[78:81], v[210:213], v[174:177], v[78:81]
	v_mfma_f32_16x16x32_bf16 v[54:57], v[210:213], v[178:181], v[54:57]
	ds_read_b128 v[210:213], v162 offset:38912
	s_waitcnt lgkmcnt(3)
	v_mfma_f32_16x16x32_bf16 v[138:141], v[214:217], v[166:169], v[138:141]
	v_mfma_f32_16x16x32_bf16 v[122:125], v[214:217], v[170:173], v[122:125]
	v_mfma_f32_16x16x32_bf16 v[74:77], v[214:217], v[174:177], v[74:77]
	v_mfma_f32_16x16x32_bf16 v[50:53], v[214:217], v[178:181], v[50:53]
	ds_read_b128 v[214:217], v162 offset:39936
	s_waitcnt lgkmcnt(3)
	v_mfma_f32_16x16x32_bf16 v[102:105], v[182:185], v[166:169], v[102:105]
	v_mfma_f32_16x16x32_bf16 v[46:49], v[182:185], v[170:173], v[46:49]
	v_mfma_f32_16x16x32_bf16 v[30:33], v[182:185], v[174:177], v[30:33]
	v_mfma_f32_16x16x32_bf16 v[14:17], v[182:185], v[178:181], v[14:17]
	s_waitcnt vmcnt(0)
	s_waitcnt lgkmcnt(2)
	v_mfma_f32_16x16x32_bf16 v[82:85], v[206:209], v[166:169], v[82:85]
	ds_write_b128 v193, v[118:121] offset:0
	v_mfma_f32_16x16x32_bf16 v[42:45], v[206:209], v[170:173], v[42:45]
	ds_write_b128 v193, v[114:117] offset:4096
	v_mfma_f32_16x16x32_bf16 v[26:29], v[206:209], v[174:177], v[26:29]
	ds_write_b128 v193, v[110:113] offset:16384
	v_mfma_f32_16x16x32_bf16 v[10:13], v[206:209], v[178:181], v[10:13]
	ds_write_b128 v193, v[106:109] offset:20480
	s_waitcnt lgkmcnt(5)
	v_mfma_f32_16x16x32_bf16 v[70:73], v[210:213], v[166:169], v[70:73]
	ds_write_b128 v193, v[90:93] offset:24576
	v_mfma_f32_16x16x32_bf16 v[38:41], v[210:213], v[170:173], v[38:41]
	ds_write_b128 v193, v[94:97] offset:28672
	v_mfma_f32_16x16x32_bf16 v[22:25], v[210:213], v[174:177], v[22:25]
	v_mfma_f32_16x16x32_bf16 v[6:9], v[210:213], v[178:181], v[6:9]
	s_waitcnt lgkmcnt(0)
	s_barrier
; #define BLOADG(kt) do { \
;     _Pragma("unroll") for (int i = 0; i < 2; ++i) ra[i] = *(const u32x4*)(ap + (size_t)(64 * i) * lda + (kt) * 32); \
;     _Pragma("unroll") for (int i = 0; i < 4; ++i) rb[i] = *(const u32x4*)(bp + (size_t)((i & 1) * s1 + (i >> 1) * s2) * ldb + (kt) * 32); } while (0)
; #define BSTOREG(st) do { \
;     _Pragma("unroll") for (int i = 0; i < 2; ++i) *(u32x4*)(sA + (st) * BGA + so + 64 * i * 32) = ra[i]; \
;     _Pragma("unroll") for (int i = 0; i < 4; ++i) *(u32x4*)(sB + (st) * BGB + so + 64 * i * 32) = rb[i]; } while (0)
;     ...
;   for (int kt = 0; kt < nk; ++kt) {
;     const int cur = kt & 1;
;     if (kt + 1 < nk) { BSTOREG(cur ^ 1); if (kt + 2 < nk) BLOADG(kt + 2); }
;     const bf16_t* cA = sA + cur * BGA + (wm * 64) * 32 + fo; const bf16_t* cB = sB + cur * BGB + (wn * 128) * 32 + fo;
;     bf16x8 af[4];
; #pragma unroll
;     for (int mi = 0; mi < 4; ++mi) af[mi] = *(const bf16x8*)(cA + mi * 16 * 32);
; #pragma unroll
;     for (int nh = 0; nh < 2; ++nh) {
;       bf16x8 bfr[4];
; #pragma unroll
;       for (int ni = 0; ni < 4; ++ni) bfr[ni] = *(const bf16x8*)(cB + (nh * 4 + ni) * 16 * 32);
; #pragma unroll
;       for (int mi = 0; mi < 4; ++mi)
; #pragma unroll
;         for (int ni = 0; ni < 4; ++ni) acc[mi][nh * 4 + ni] = __builtin_amdgcn_mfma_f32_16x16x32_bf16(bfr[ni], af[mi], acc[mi][nh * 4 + ni], 0, 0, 0);
;     }
;     __syncthreads();
	v_mfma_f32_16x16x32_bf16 v[58:61], v[214:217], v[166:169], v[58:61]
	v_mfma_f32_16x16x32_bf16 v[34:37], v[214:217], v[170:173], v[34:37]
	v_mfma_f32_16x16x32_bf16 v[18:21], v[214:217], v[174:177], v[18:21]
	v_mfma_f32_16x16x32_bf16 v[2:5], v[214:217], v[178:181], v[2:5]
	ds_read_b128 v[166:169], v192 offset:33792
	ds_read_b128 v[170:173], v192 offset:34816
	ds_read_b128 v[174:177], v192 offset:35840
	ds_read_b128 v[178:181], v192 offset:36864
	ds_read_b128 v[182:185], v162 offset:49152
	ds_read_b128 v[206:209], v162 offset:50176
	ds_read_b128 v[210:213], v162 offset:51200
	ds_read_b128 v[214:217], v162 offset:52224
	s_waitcnt lgkmcnt(7)
	s_waitcnt lgkmcnt(3)
	v_mfma_f32_16x16x32_bf16 v[150:153], v[182:185], v[166:169], v[150:153]
	v_mfma_f32_16x16x32_bf16 v[134:137], v[182:185], v[170:173], v[134:137]
	v_mfma_f32_16x16x32_bf16 v[98:101], v[182:185], v[174:177], v[98:101]
	v_mfma_f32_16x16x32_bf16 v[66:69], v[182:185], v[178:181], v[66:69]
	ds_read_b128 v[182:185], v162 offset:53248
	s_sub_u32 m0, m0, 0xd000
	s_nop 0
	global_load_lds_dwordx4 v218, s[26:27]
	global_load_dwordx4 v[118:121], v218, s[26:27] offset:64
	s_waitcnt lgkmcnt(3)
	v_mfma_f32_16x16x32_bf16 v[146:149], v[206:209], v[166:169], v[146:149]
	v_mfma_f32_16x16x32_bf16 v[130:133], v[206:209], v[170:173], v[130:133]
	v_mfma_f32_16x16x32_bf16 v[86:89], v[206:209], v[174:177], v[86:89]
	v_mfma_f32_16x16x32_bf16 v[62:65], v[206:209], v[178:181], v[62:65]
	ds_read_b128 v[206:209], v162 offset:54272
	s_add_u32 m0, m0, 0x1000
	s_nop 0
	global_load_lds_dwordx4 v219, s[26:27]
	global_load_dwordx4 v[114:117], v219, s[26:27] offset:64
	s_waitcnt lgkmcnt(3)
	v_mfma_f32_16x16x32_bf16 v[142:145], v[210:213], v[166:169], v[142:145]
	v_mfma_f32_16x16x32_bf16 v[126:129], v[210:213], v[170:173], v[126:129]
	v_mfma_f32_16x16x32_bf16 v[78:81], v[210:213], v[174:177], v[78:81]
	v_mfma_f32_16x16x32_bf16 v[54:57], v[210:213], v[178:181], v[54:57]
	ds_read_b128 v[210:213], v162 offset:55296
	s_add_u32 m0, m0, 0x5000
	s_nop 0
	global_load_lds_dwordx4 v220, s[28:29]
	global_load_dwordx4 v[110:113], v220, s[28:29] offset:64
	s_waitcnt lgkmcnt(3)
	v_mfma_f32_16x16x32_bf16 v[138:141], v[214:217], v[166:169], v[138:141]
	v_mfma_f32_16x16x32_bf16 v[122:125], v[214:217], v[170:173], v[122:125]
	v_mfma_f32_16x16x32_bf16 v[74:77], v[214:217], v[174:177], v[74:77]
	v_mfma_f32_16x16x32_bf16 v[50:53], v[214:217], v[178:181], v[50:53]
	ds_read_b128 v[214:217], v162 offset:56320
	s_add_u32 m0, m0, 0x1000
	s_nop 0
	global_load_lds_dwordx4 v221, s[28:29]
	global_load_dwordx4 v[106:109], v221, s[28:29] offset:64
	s_waitcnt lgkmcnt(3)
	v_mfma_f32_16x16x32_bf16 v[102:105], v[182:185], v[166:169], v[102:105]
	v_mfma_f32_16x16x32_bf16 v[46:49], v[182:185], v[170:173], v[46:49]
	v_mfma_f32_16x16x32_bf16 v[30:33], v[182:185], v[174:177], v[30:33]
	v_mfma_f32_16x16x32_bf16 v[14:17], v[182:185], v[178:181], v[14:17]
	s_add_u32 m0, m0, 0x1000
	s_nop 0
	global_load_lds_dwordx4 v190, s[28:29]
	global_load_dwordx4 v[90:93], v190, s[28:29] offset:64
	s_waitcnt lgkmcnt(2)
	v_mfma_f32_16x16x32_bf16 v[82:85], v[206:209], v[166:169], v[82:85]
	v_mfma_f32_16x16x32_bf16 v[42:45], v[206:209], v[170:173], v[42:45]
	v_mfma_f32_16x16x32_bf16 v[26:29], v[206:209], v[174:177], v[26:29]
	v_mfma_f32_16x16x32_bf16 v[10:13], v[206:209], v[178:181], v[10:13]
	s_add_u32 m0, m0, 0x1000
	s_nop 0
	global_load_lds_dwordx4 v191, s[28:29]
	global_load_dwordx4 v[94:97], v191, s[28:29] offset:64
	s_add_u32 s26, s26, 0x80
	s_addc_u32 s27, s27, 0
	s_add_u32 s28, s28, 0x80
	s_addc_u32 s29, s29, 0
	s_waitcnt lgkmcnt(1)
	v_mfma_f32_16x16x32_bf16 v[70:73], v[210:213], v[166:169], v[70:73]
	v_mfma_f32_16x16x32_bf16 v[38:41], v[210:213], v[170:173], v[38:41]
	v_mfma_f32_16x16x32_bf16 v[22:25], v[210:213], v[174:177], v[22:25]
	v_mfma_f32_16x16x32_bf16 v[6:9], v[210:213], v[178:181], v[6:9]
	s_waitcnt lgkmcnt(0)
	s_barrier
	v_mfma_f32_16x16x32_bf16 v[58:61], v[214:217], v[166:169], v[58:61]
	v_mfma_f32_16x16x32_bf16 v[34:37], v[214:217], v[170:173], v[34:37]
	v_mfma_f32_16x16x32_bf16 v[18:21], v[214:217], v[174:177], v[18:21]
	v_mfma_f32_16x16x32_bf16 v[2:5], v[214:217], v[178:181], v[2:5]
	ds_read_b128 v[166:169], v163 offset:0
	ds_read_b128 v[170:173], v163 offset:1024
	ds_read_b128 v[174:177], v163 offset:2048
	ds_read_b128 v[178:181], v163 offset:3072
	ds_read_b128 v[182:185], v162 offset:16384
	ds_read_b128 v[206:209], v162 offset:17408
	ds_read_b128 v[210:213], v162 offset:18432
	ds_read_b128 v[214:217], v162 offset:19456
	s_waitcnt lgkmcnt(7)
	s_waitcnt lgkmcnt(3)
	v_mfma_f32_16x16x32_bf16 v[150:153], v[182:185], v[166:169], v[150:153]
	v_mfma_f32_16x16x32_bf16 v[134:137], v[182:185], v[170:173], v[134:137]
	v_mfma_f32_16x16x32_bf16 v[98:101], v[182:185], v[174:177], v[98:101]
	v_mfma_f32_16x16x32_bf16 v[66:69], v[182:185], v[178:181], v[66:69]
	ds_read_b128 v[182:185], v162 offset:20480
	s_waitcnt lgkmcnt(3)
	v_mfma_f32_16x16x32_bf16 v[146:149], v[206:209], v[166:169], v[146:149]
	v_mfma_f32_16x16x32_bf16 v[130:133], v[206:209], v[170:173], v[130:133]
	v_mfma_f32_16x16x32_bf16 v[86:89], v[206:209], v[174:177], v[86:89]
	v_mfma_f32_16x16x32_bf16 v[62:65], v[206:209], v[178:181], v[62:65]
	ds_read_b128 v[206:209], v162 offset:21504
	s_waitcnt lgkmcnt(3)
	v_mfma_f32_16x16x32_bf16 v[142:145], v[210:213], v[166:169], v[142:145]
	v_mfma_f32_16x16x32_bf16 v[126:129], v[210:213], v[170:173], v[126:129]
	v_mfma_f32_16x16x32_bf16 v[78:81], v[210:213], v[174:177], v[78:81]
	v_mfma_f32_16x16x32_bf16 v[54:57], v[210:213], v[178:181], v[54:57]
	ds_read_b128 v[210:213], v162 offset:22528
	s_waitcnt lgkmcnt(3)
; #define BLOADG(kt) do { \
;     _Pragma("unroll") for (int i = 0; i < 2; ++i) ra[i] = *(const u32x4*)(ap + (size_t)(64 * i) * lda + (kt) * 32); \
;     _Pragma("unroll") for (int i = 0; i < 4; ++i) rb[i] = *(const u32x4*)(bp + (size_t)((i & 1) * s1 + (i >> 1) * s2) * ldb + (kt) * 32); } while (0)
; #define BSTOREG(st) do { \
;     _Pragma("unroll") for (int i = 0; i < 2; ++i) *(u32x4*)(sA + (st) * BGA + so + 64 * i * 32) = ra[i]; \
;     _Pragma("unroll") for (int i = 0; i < 4; ++i) *(u32x4*)(sB + (st) * BGB + so + 64 * i * 32) = rb[i]; } while (0)
;     ...
;   for (int kt = 0; kt < nk; ++kt) {
;     const int cur = kt & 1;
;     if (kt + 1 < nk) { BSTOREG(cur ^ 1); if (kt + 2 < nk) BLOADG(kt + 2); }
;     const bf16_t* cA = sA + cur * BGA + (wm * 64) * 32 + fo; const bf16_t* cB = sB + cur * BGB + (wn * 128) * 32 + fo;
;     bf16x8 af[4];
; #pragma unroll
;     for (int mi = 0; mi < 4; ++mi) af[mi] = *(const bf16x8*)(cA + mi * 16 * 32);
; #pragma unroll
;     for (int nh = 0; nh < 2; ++nh) {
;       bf16x8 bfr[4];
; #pragma unroll
;       for (int ni = 0; ni < 4; ++ni) bfr[ni] = *(const bf16x8*)(cB + (nh * 4 + ni) * 16 * 32);
; #pragma unroll
;       for (int mi = 0; mi < 4; ++mi)
; #pragma unroll
;         for (int ni = 0; ni < 4; ++ni) acc[mi][nh * 4 + ni] = __builtin_amdgcn_mfma_f32_16x16x32_bf16(bfr[ni], af[mi], acc[mi][nh * 4 + ni], 0, 0, 0);
;     }
;     __syncthreads();
	v_mfma_f32_16x16x32_bf16 v[138:141], v[214:217], v[166:169], v[138:141]
	v_mfma_f32_16x16x32_bf16 v[122:125], v[214:217], v[170:173], v[122:125]
	v_mfma_f32_16x16x32_bf16 v[74:77], v[214:217], v[174:177], v[74:77]
	v_mfma_f32_16x16x32_bf16 v[50:53], v[214:217], v[178:181], v[50:53]
	ds_read_b128 v[214:217], v162 offset:23552
	s_waitcnt lgkmcnt(3)
	v_mfma_f32_16x16x32_bf16 v[102:105], v[182:185], v[166:169], v[102:105]
	v_mfma_f32_16x16x32_bf16 v[46:49], v[182:185], v[170:173], v[46:49]
	v_mfma_f32_16x16x32_bf16 v[30:33], v[182:185], v[174:177], v[30:33]
	v_mfma_f32_16x16x32_bf16 v[14:17], v[182:185], v[178:181], v[14:17]
	s_waitcnt vmcnt(0)
	s_waitcnt lgkmcnt(2)
	v_mfma_f32_16x16x32_bf16 v[82:85], v[206:209], v[166:169], v[82:85]
	ds_write_b128 v194, v[118:121] offset:33792
	v_mfma_f32_16x16x32_bf16 v[42:45], v[206:209], v[170:173], v[42:45]
	ds_write_b128 v194, v[114:117] offset:37888
	v_mfma_f32_16x16x32_bf16 v[26:29], v[206:209], v[174:177], v[26:29]
	ds_write_b128 v193, v[110:113] offset:49152
	v_mfma_f32_16x16x32_bf16 v[10:13], v[206:209], v[178:181], v[10:13]
	ds_write_b128 v193, v[106:109] offset:53248
	s_waitcnt lgkmcnt(5)
	v_mfma_f32_16x16x32_bf16 v[70:73], v[210:213], v[166:169], v[70:73]
	ds_write_b128 v193, v[90:93] offset:57344
	v_mfma_f32_16x16x32_bf16 v[38:41], v[210:213], v[170:173], v[38:41]
	ds_write_b128 v194, v[94:97] offset:28672
	v_mfma_f32_16x16x32_bf16 v[22:25], v[210:213], v[174:177], v[22:25]
	v_mfma_f32_16x16x32_bf16 v[6:9], v[210:213], v[178:181], v[6:9]
	s_waitcnt lgkmcnt(0)
	s_barrier
	v_mfma_f32_16x16x32_bf16 v[58:61], v[214:217], v[166:169], v[58:61]
	v_mfma_f32_16x16x32_bf16 v[34:37], v[214:217], v[170:173], v[34:37]
	v_mfma_f32_16x16x32_bf16 v[18:21], v[214:217], v[174:177], v[18:21]
	v_mfma_f32_16x16x32_bf16 v[2:5], v[214:217], v[178:181], v[2:5]
	ds_read_b128 v[166:169], v163 offset:8192
	ds_read_b128 v[170:173], v163 offset:9216
	ds_read_b128 v[174:177], v163 offset:10240
	ds_read_b128 v[178:181], v163 offset:11264
	ds_read_b128 v[182:185], v162 offset:32768
	ds_read_b128 v[206:209], v162 offset:33792
	ds_read_b128 v[210:213], v162 offset:34816
	ds_read_b128 v[214:217], v162 offset:35840
	s_waitcnt lgkmcnt(7)
	s_waitcnt lgkmcnt(3)
	v_mfma_f32_16x16x32_bf16 v[150:153], v[182:185], v[166:169], v[150:153]
	v_mfma_f32_16x16x32_bf16 v[134:137], v[182:185], v[170:173], v[134:137]
	v_mfma_f32_16x16x32_bf16 v[98:101], v[182:185], v[174:177], v[98:101]
	v_mfma_f32_16x16x32_bf16 v[66:69], v[182:185], v[178:181], v[66:69]
	ds_read_b128 v[182:185], v162 offset:36864
	s_sub_u32 m0, m0, 0xb000
	s_nop 0
	global_load_lds_dwordx4 v218, s[26:27]
	global_load_dwordx4 v[118:121], v218, s[26:27] offset:64
	s_waitcnt lgkmcnt(3)
	v_mfma_f32_16x16x32_bf16 v[146:149], v[206:209], v[166:169], v[146:149]
	v_mfma_f32_16x16x32_bf16 v[130:133], v[206:209], v[170:173], v[130:133]
	v_mfma_f32_16x16x32_bf16 v[86:89], v[206:209], v[174:177], v[86:89]
	v_mfma_f32_16x16x32_bf16 v[62:65], v[206:209], v[178:181], v[62:65]
	ds_read_b128 v[206:209], v162 offset:37888
	s_add_u32 m0, m0, 0x1000
	s_nop 0
	global_load_lds_dwordx4 v219, s[26:27]
	global_load_dwordx4 v[114:117], v219, s[26:27] offset:64
	s_waitcnt lgkmcnt(3)
	v_mfma_f32_16x16x32_bf16 v[142:145], v[210:213], v[166:169], v[142:145]
	v_mfma_f32_16x16x32_bf16 v[126:129], v[210:213], v[170:173], v[126:129]
	v_mfma_f32_16x16x32_bf16 v[78:81], v[210:213], v[174:177], v[78:81]
	v_mfma_f32_16x16x32_bf16 v[54:57], v[210:213], v[178:181], v[54:57]
	ds_read_b128 v[210:213], v162 offset:38912
	s_add_u32 m0, m0, 0x3000
	s_nop 0
	global_load_lds_dwordx4 v220, s[28:29]
	global_load_dwordx4 v[110:113], v220, s[28:29] offset:64
	s_waitcnt lgkmcnt(3)
	v_mfma_f32_16x16x32_bf16 v[138:141], v[214:217], v[166:169], v[138:141]
	v_mfma_f32_16x16x32_bf16 v[122:125], v[214:217], v[170:173], v[122:125]
	v_mfma_f32_16x16x32_bf16 v[74:77], v[214:217], v[174:177], v[74:77]
	v_mfma_f32_16x16x32_bf16 v[50:53], v[214:217], v[178:181], v[50:53]
	ds_read_b128 v[214:217], v162 offset:39936
	s_add_u32 m0, m0, 0x1000
	s_nop 0
	global_load_lds_dwordx4 v221, s[28:29]
	global_load_dwordx4 v[106:109], v221, s[28:29] offset:64
	s_waitcnt lgkmcnt(3)
	v_mfma_f32_16x16x32_bf16 v[102:105], v[182:185], v[166:169], v[102:105]
	v_mfma_f32_16x16x32_bf16 v[46:49], v[182:185], v[170:173], v[46:49]
	v_mfma_f32_16x16x32_bf16 v[30:33], v[182:185], v[174:177], v[30:33]
	v_mfma_f32_16x16x32_bf16 v[14:17], v[182:185], v[178:181], v[14:17]
	s_add_u32 m0, m0, 0x1000
	s_nop 0
	global_load_lds_dwordx4 v190, s[28:29]
	global_load_dwordx4 v[90:93], v190, s[28:29] offset:64
	s_waitcnt lgkmcnt(2)
	v_mfma_f32_16x16x32_bf16 v[82:85], v[206:209], v[166:169], v[82:85]
	v_mfma_f32_16x16x32_bf16 v[42:45], v[206:209], v[170:173], v[42:45]
	v_mfma_f32_16x16x32_bf16 v[26:29], v[206:209], v[174:177], v[26:29]
	v_mfma_f32_16x16x32_bf16 v[10:13], v[206:209], v[178:181], v[10:13]
	s_add_u32 m0, m0, 0x1000
	s_nop 0
	global_load_lds_dwordx4 v191, s[28:29]
	global_load_dwordx4 v[94:97], v191, s[28:29] offset:64
	s_add_u32 s26, s26, 0x80
	s_addc_u32 s27, s27, 0
	s_add_u32 s28, s28, 0x80
	s_addc_u32 s29, s29, 0
	s_waitcnt lgkmcnt(1)
	v_mfma_f32_16x16x32_bf16 v[70:73], v[210:213], v[166:169], v[70:73]
	v_mfma_f32_16x16x32_bf16 v[38:41], v[210:213], v[170:173], v[38:41]
	v_mfma_f32_16x16x32_bf16 v[22:25], v[210:213], v[174:177], v[22:25]
	v_mfma_f32_16x16x32_bf16 v[6:9], v[210:213], v[178:181], v[6:9]
	s_waitcnt lgkmcnt(0)
	s_barrier
; #define BLOADG(kt) do { \
;     _Pragma("unroll") for (int i = 0; i < 2; ++i) ra[i] = *(const u32x4*)(ap + (size_t)(64 * i) * lda + (kt) * 32); \
;     _Pragma("unroll") for (int i = 0; i < 4; ++i) rb[i] = *(const u32x4*)(bp + (size_t)((i & 1) * s1 + (i >> 1) * s2) * ldb + (kt) * 32); } while (0)
; #define BSTOREG(st) do { \
;     _Pragma("unroll") for (int i = 0; i < 2; ++i) *(u32x4*)(sA + (st) * BGA + so + 64 * i * 32) = ra[i]; \
;     _Pragma("unroll") for (int i = 0; i < 4; ++i) *(u32x4*)(sB + (st) * BGB + so + 64 * i * 32) = rb[i]; } while (0)
;     ...
;   for (int kt = 0; kt < nk; ++kt) {
;     const int cur = kt & 1;
;     if (kt + 1 < nk) { BSTOREG(cur ^ 1); if (kt + 2 < nk) BLOADG(kt + 2); }
;     const bf16_t* cA = sA + cur * BGA + (wm * 64) * 32 + fo; const bf16_t* cB = sB + cur * BGB + (wn * 128) * 32 + fo;
;     bf16x8 af[4];
; #pragma unroll
;     for (int mi = 0; mi < 4; ++mi) af[mi] = *(const bf16x8*)(cA + mi * 16 * 32);
; #pragma unroll
;     for (int nh = 0; nh < 2; ++nh) {
;       bf16x8 bfr[4];
; #pragma unroll
;       for (int ni = 0; ni < 4; ++ni) bfr[ni] = *(const bf16x8*)(cB + (nh * 4 + ni) * 16 * 32);
; #pragma unroll
;       for (int mi = 0; mi < 4; ++mi)
; #pragma unroll
;         for (int ni = 0; ni < 4; ++ni) acc[mi][nh * 4 + ni] = __builtin_amdgcn_mfma_f32_16x16x32_bf16(bfr[ni], af[mi], acc[mi][nh * 4 + ni], 0, 0, 0);
;     }
;     __syncthreads();
	v_mfma_f32_16x16x32_bf16 v[58:61], v[214:217], v[166:169], v[58:61]
	v_mfma_f32_16x16x32_bf16 v[34:37], v[214:217], v[170:173], v[34:37]
	v_mfma_f32_16x16x32_bf16 v[18:21], v[214:217], v[174:177], v[18:21]
	v_mfma_f32_16x16x32_bf16 v[2:5], v[214:217], v[178:181], v[2:5]
	ds_read_b128 v[166:169], v192 offset:33792
	ds_read_b128 v[170:173], v192 offset:34816
	ds_read_b128 v[174:177], v192 offset:35840
	ds_read_b128 v[178:181], v192 offset:36864
	ds_read_b128 v[182:185], v162 offset:49152
	ds_read_b128 v[206:209], v162 offset:50176
	ds_read_b128 v[210:213], v162 offset:51200
	ds_read_b128 v[214:217], v162 offset:52224
	s_waitcnt lgkmcnt(7)
	s_waitcnt lgkmcnt(3)
	v_mfma_f32_16x16x32_bf16 v[150:153], v[182:185], v[166:169], v[150:153]
	v_mfma_f32_16x16x32_bf16 v[134:137], v[182:185], v[170:173], v[134:137]
	v_mfma_f32_16x16x32_bf16 v[98:101], v[182:185], v[174:177], v[98:101]
	v_mfma_f32_16x16x32_bf16 v[66:69], v[182:185], v[178:181], v[66:69]
	ds_read_b128 v[182:185], v162 offset:53248
	s_waitcnt lgkmcnt(3)
	v_mfma_f32_16x16x32_bf16 v[146:149], v[206:209], v[166:169], v[146:149]
	v_mfma_f32_16x16x32_bf16 v[130:133], v[206:209], v[170:173], v[130:133]
	v_mfma_f32_16x16x32_bf16 v[86:89], v[206:209], v[174:177], v[86:89]
	v_mfma_f32_16x16x32_bf16 v[62:65], v[206:209], v[178:181], v[62:65]
	ds_read_b128 v[206:209], v162 offset:54272
	s_waitcnt lgkmcnt(3)
	v_mfma_f32_16x16x32_bf16 v[142:145], v[210:213], v[166:169], v[142:145]
	v_mfma_f32_16x16x32_bf16 v[126:129], v[210:213], v[170:173], v[126:129]
	v_mfma_f32_16x16x32_bf16 v[78:81], v[210:213], v[174:177], v[78:81]
	v_mfma_f32_16x16x32_bf16 v[54:57], v[210:213], v[178:181], v[54:57]
	ds_read_b128 v[210:213], v162 offset:55296
	s_waitcnt lgkmcnt(3)
	v_mfma_f32_16x16x32_bf16 v[138:141], v[214:217], v[166:169], v[138:141]
	v_mfma_f32_16x16x32_bf16 v[122:125], v[214:217], v[170:173], v[122:125]
	v_mfma_f32_16x16x32_bf16 v[74:77], v[214:217], v[174:177], v[74:77]
	v_mfma_f32_16x16x32_bf16 v[50:53], v[214:217], v[178:181], v[50:53]
	ds_read_b128 v[214:217], v162 offset:56320
	s_waitcnt lgkmcnt(3)
	v_mfma_f32_16x16x32_bf16 v[102:105], v[182:185], v[166:169], v[102:105]
	v_mfma_f32_16x16x32_bf16 v[46:49], v[182:185], v[170:173], v[46:49]
	v_mfma_f32_16x16x32_bf16 v[30:33], v[182:185], v[174:177], v[30:33]
	v_mfma_f32_16x16x32_bf16 v[14:17], v[182:185], v[178:181], v[14:17]
	s_waitcnt vmcnt(0)
	s_waitcnt lgkmcnt(2)
	v_mfma_f32_16x16x32_bf16 v[82:85], v[206:209], v[166:169], v[82:85]
	ds_write_b128 v193, v[118:121] offset:8192
	v_mfma_f32_16x16x32_bf16 v[42:45], v[206:209], v[170:173], v[42:45]
	ds_write_b128 v193, v[114:117] offset:12288
	v_mfma_f32_16x16x32_bf16 v[26:29], v[206:209], v[174:177], v[26:29]
	ds_write_b128 v193, v[110:113] offset:32768
	v_mfma_f32_16x16x32_bf16 v[10:13], v[206:209], v[178:181], v[10:13]
	ds_write_b128 v193, v[106:109] offset:36864
	s_waitcnt lgkmcnt(5)
	v_mfma_f32_16x16x32_bf16 v[70:73], v[210:213], v[166:169], v[70:73]
	ds_write_b128 v193, v[90:93] offset:40960
	v_mfma_f32_16x16x32_bf16 v[38:41], v[210:213], v[170:173], v[38:41]
	ds_write_b128 v193, v[94:97] offset:45056
	v_mfma_f32_16x16x32_bf16 v[22:25], v[210:213], v[174:177], v[22:25]
	v_mfma_f32_16x16x32_bf16 v[6:9], v[210:213], v[178:181], v[6:9]
	s_waitcnt lgkmcnt(0)
	s_barrier
	v_mfma_f32_16x16x32_bf16 v[58:61], v[214:217], v[166:169], v[58:61]
	v_mfma_f32_16x16x32_bf16 v[34:37], v[214:217], v[170:173], v[34:37]
	v_mfma_f32_16x16x32_bf16 v[18:21], v[214:217], v[174:177], v[18:21]
	v_mfma_f32_16x16x32_bf16 v[2:5], v[214:217], v[178:181], v[2:5]
	s_add_i32 s22, s22, 1
	s_cmp_lg_u32 s22, 5
	s_cbranch_scc1 .LBB0_238
	ds_read_b128 v[166:169], v163 offset:0
	ds_read_b128 v[170:173], v163 offset:1024
	ds_read_b128 v[174:177], v163 offset:2048
	ds_read_b128 v[178:181], v163 offset:3072
	ds_read_b128 v[182:185], v162 offset:16384
	ds_read_b128 v[206:209], v162 offset:17408
	ds_read_b128 v[210:213], v162 offset:18432
	ds_read_b128 v[214:217], v162 offset:19456
	s_waitcnt lgkmcnt(7)
	s_waitcnt lgkmcnt(3)
	v_mfma_f32_16x16x32_bf16 v[150:153], v[182:185], v[166:169], v[150:153]
	v_mfma_f32_16x16x32_bf16 v[134:137], v[182:185], v[170:173], v[134:137]
	v_mfma_f32_16x16x32_bf16 v[98:101], v[182:185], v[174:177], v[98:101]
	v_mfma_f32_16x16x32_bf16 v[66:69], v[182:185], v[178:181], v[66:69]
	ds_read_b128 v[182:185], v162 offset:20480
	s_waitcnt lgkmcnt(3)
	v_mfma_f32_16x16x32_bf16 v[146:149], v[206:209], v[166:169], v[146:149]
	v_mfma_f32_16x16x32_bf16 v[130:133], v[206:209], v[170:173], v[130:133]
	v_mfma_f32_16x16x32_bf16 v[86:89], v[206:209], v[174:177], v[86:89]
	v_mfma_f32_16x16x32_bf16 v[62:65], v[206:209], v[178:181], v[62:65]
	ds_read_b128 v[206:209], v162 offset:21504
	s_waitcnt lgkmcnt(3)
	v_mfma_f32_16x16x32_bf16 v[142:145], v[210:213], v[166:169], v[142:145]
	v_mfma_f32_16x16x32_bf16 v[126:129], v[210:213], v[170:173], v[126:129]
	v_mfma_f32_16x16x32_bf16 v[78:81], v[210:213], v[174:177], v[78:81]
	v_mfma_f32_16x16x32_bf16 v[54:57], v[210:213], v[178:181], v[54:57]
	ds_read_b128 v[210:213], v162 offset:22528
	s_waitcnt lgkmcnt(3)
	v_mfma_f32_16x16x32_bf16 v[138:141], v[214:217], v[166:169], v[138:141]
	v_mfma_f32_16x16x32_bf16 v[122:125], v[214:217], v[170:173], v[122:125]
	v_mfma_f32_16x16x32_bf16 v[74:77], v[214:217], v[174:177], v[74:77]
	v_mfma_f32_16x16x32_bf16 v[50:53], v[214:217], v[178:181], v[50:53]
	ds_read_b128 v[214:217], v162 offset:23552
	s_waitcnt lgkmcnt(3)
	v_mfma_f32_16x16x32_bf16 v[102:105], v[182:185], v[166:169], v[102:105]
	v_mfma_f32_16x16x32_bf16 v[46:49], v[182:185], v[170:173], v[46:49]
	v_mfma_f32_16x16x32_bf16 v[30:33], v[182:185], v[174:177], v[30:33]
	v_mfma_f32_16x16x32_bf16 v[14:17], v[182:185], v[178:181], v[14:17]
	s_waitcnt lgkmcnt(2)
; DI int otid() { int t; asm volatile("v_mov_b32 %0, %1" : "=v"(t) : "v"((int)threadIdx.x)); __builtin_assume(t >= 0 && t < 256); return t; }
; #define BLOADG(kt) do { \
;     _Pragma("unroll") for (int i = 0; i < 2; ++i) ra[i] = *(const u32x4*)(ap + (size_t)(64 * i) * lda + (kt) * 32); \
;     _Pragma("unroll") for (int i = 0; i < 4; ++i) rb[i] = *(const u32x4*)(bp + (size_t)((i & 1) * s1 + (i >> 1) * s2) * ldb + (kt) * 32); } while (0)
; #define BSTOREG(st) do { \
;     _Pragma("unroll") for (int i = 0; i < 2; ++i) *(u32x4*)(sA + (st) * BGA + so + 64 * i * 32) = ra[i]; \
;     _Pragma("unroll") for (int i = 0; i < 4; ++i) *(u32x4*)(sB + (st) * BGB + so + 64 * i * 32) = rb[i]; } while (0)
;     ...
;   for (int kt = 0; kt < nk; ++kt) {
;     const int cur = kt & 1;
;     if (kt + 1 < nk) { BSTOREG(cur ^ 1); if (kt + 2 < nk) BLOADG(kt + 2); }
;     const bf16_t* cA = sA + cur * BGA + (wm * 64) * 32 + fo; const bf16_t* cB = sB + cur * BGB + (wn * 128) * 32 + fo;
;     bf16x8 af[4];
; #pragma unroll
;     for (int mi = 0; mi < 4; ++mi) af[mi] = *(const bf16x8*)(cA + mi * 16 * 32);
; #pragma unroll
;     for (int nh = 0; nh < 2; ++nh) {
;       bf16x8 bfr[4];
; #pragma unroll
;       for (int ni = 0; ni < 4; ++ni) bfr[ni] = *(const bf16x8*)(cB + (nh * 4 + ni) * 16 * 32);
; #pragma unroll
;       for (int mi = 0; mi < 4; ++mi)
; #pragma unroll
;         for (int ni = 0; ni < 4; ++ni) acc[mi][nh * 4 + ni] = __builtin_amdgcn_mfma_f32_16x16x32_bf16(bfr[ni], af[mi], acc[mi][nh * 4 + ni], 0, 0, 0);
;     }
;     __syncthreads();
; DI void outproj_tile(const Params& p, int l, int tile, char* smem) {
;     ...
;   const float* xin = l == 0 ? p.x : p.out;
;   const int lane = otid() & 63, wid = otid() >> 6, wm = wid >> 1, wn = wid & 1, fr = lane & 15, fq = lane >> 4;
; #pragma unroll
;   for (int mi = 0; mi < 4; ++mi)
; #pragma unroll
;     for (int ni = 0; ni < 8; ++ni) {
;       size_t row = (size_t)mt * 128 + wm * 64 + mi * 16 + fr; int col = nt * 256 + wn * 128 + ni * 16 + fq * 4;
;       float4 xi = *(const float4*)(xin + row * 1024 + col);
;       float4 o; o.x = xi.x + acc[mi][ni][0]; o.y = xi.y + acc[mi][ni][1]; o.z = xi.z + acc[mi][ni][2]; o.w = xi.w + acc[mi][ni][3];
;       *(float4*)(p.out + row * 1024 + col) = o;
	v_mfma_f32_16x16x32_bf16 v[82:85], v[206:209], v[166:169], v[82:85]
	v_mfma_f32_16x16x32_bf16 v[42:45], v[206:209], v[170:173], v[42:45]
	v_mfma_f32_16x16x32_bf16 v[26:29], v[206:209], v[174:177], v[26:29]
	v_mfma_f32_16x16x32_bf16 v[10:13], v[206:209], v[178:181], v[10:13]
	s_waitcnt lgkmcnt(1)
	v_mfma_f32_16x16x32_bf16 v[70:73], v[210:213], v[166:169], v[70:73]
	v_mfma_f32_16x16x32_bf16 v[38:41], v[210:213], v[170:173], v[38:41]
	v_mfma_f32_16x16x32_bf16 v[22:25], v[210:213], v[174:177], v[22:25]
	v_mfma_f32_16x16x32_bf16 v[6:9], v[210:213], v[178:181], v[6:9]
	s_waitcnt lgkmcnt(0)
	v_mfma_f32_16x16x32_bf16 v[58:61], v[214:217], v[166:169], v[58:61]
	v_mfma_f32_16x16x32_bf16 v[34:37], v[214:217], v[170:173], v[34:37]
	v_mfma_f32_16x16x32_bf16 v[18:21], v[214:217], v[174:177], v[18:21]
	v_mfma_f32_16x16x32_bf16 v[2:5], v[214:217], v[178:181], v[2:5]
	ds_read_b128 v[166:169], v163 offset:8192
	ds_read_b128 v[170:173], v163 offset:9216
	ds_read_b128 v[174:177], v163 offset:10240
	ds_read_b128 v[178:181], v163 offset:11264
	ds_read_b128 v[182:185], v162 offset:32768
	ds_read_b128 v[206:209], v162 offset:33792
	ds_read_b128 v[210:213], v162 offset:34816
	ds_read_b128 v[214:217], v162 offset:35840
	s_waitcnt lgkmcnt(7)
	s_waitcnt lgkmcnt(3)
	v_mfma_f32_16x16x32_bf16 v[150:153], v[182:185], v[166:169], v[150:153]
	v_mfma_f32_16x16x32_bf16 v[134:137], v[182:185], v[170:173], v[134:137]
	v_mfma_f32_16x16x32_bf16 v[98:101], v[182:185], v[174:177], v[98:101]
	v_mfma_f32_16x16x32_bf16 v[66:69], v[182:185], v[178:181], v[66:69]
	ds_read_b128 v[182:185], v162 offset:36864
	s_waitcnt lgkmcnt(3)
	v_mfma_f32_16x16x32_bf16 v[146:149], v[206:209], v[166:169], v[146:149]
	v_mfma_f32_16x16x32_bf16 v[130:133], v[206:209], v[170:173], v[130:133]
	v_mfma_f32_16x16x32_bf16 v[86:89], v[206:209], v[174:177], v[86:89]
	v_mfma_f32_16x16x32_bf16 v[62:65], v[206:209], v[178:181], v[62:65]
	ds_read_b128 v[206:209], v162 offset:37888
	s_waitcnt lgkmcnt(3)
	v_mfma_f32_16x16x32_bf16 v[142:145], v[210:213], v[166:169], v[142:145]
	v_mfma_f32_16x16x32_bf16 v[126:129], v[210:213], v[170:173], v[126:129]
	v_mfma_f32_16x16x32_bf16 v[78:81], v[210:213], v[174:177], v[78:81]
	v_mfma_f32_16x16x32_bf16 v[54:57], v[210:213], v[178:181], v[54:57]
	ds_read_b128 v[210:213], v162 offset:38912
	s_waitcnt lgkmcnt(3)
	v_mfma_f32_16x16x32_bf16 v[138:141], v[214:217], v[166:169], v[138:141]
	v_mfma_f32_16x16x32_bf16 v[122:125], v[214:217], v[170:173], v[122:125]
	v_mfma_f32_16x16x32_bf16 v[74:77], v[214:217], v[174:177], v[74:77]
	v_mfma_f32_16x16x32_bf16 v[50:53], v[214:217], v[178:181], v[50:53]
	ds_read_b128 v[214:217], v162 offset:39936
	s_waitcnt lgkmcnt(3)
	v_mfma_f32_16x16x32_bf16 v[102:105], v[182:185], v[166:169], v[102:105]
	v_mfma_f32_16x16x32_bf16 v[46:49], v[182:185], v[170:173], v[46:49]
	v_mfma_f32_16x16x32_bf16 v[30:33], v[182:185], v[174:177], v[30:33]
	v_mfma_f32_16x16x32_bf16 v[14:17], v[182:185], v[178:181], v[14:17]
	s_waitcnt lgkmcnt(2)
	v_mfma_f32_16x16x32_bf16 v[82:85], v[206:209], v[166:169], v[82:85]
	v_mfma_f32_16x16x32_bf16 v[42:45], v[206:209], v[170:173], v[42:45]
	v_mfma_f32_16x16x32_bf16 v[26:29], v[206:209], v[174:177], v[26:29]
	v_mfma_f32_16x16x32_bf16 v[10:13], v[206:209], v[178:181], v[10:13]
	s_waitcnt lgkmcnt(1)
	v_mfma_f32_16x16x32_bf16 v[70:73], v[210:213], v[166:169], v[70:73]
	v_mfma_f32_16x16x32_bf16 v[38:41], v[210:213], v[170:173], v[38:41]
	v_mfma_f32_16x16x32_bf16 v[22:25], v[210:213], v[174:177], v[22:25]
	v_mfma_f32_16x16x32_bf16 v[6:9], v[210:213], v[178:181], v[6:9]
	s_waitcnt lgkmcnt(0)
	v_mfma_f32_16x16x32_bf16 v[58:61], v[214:217], v[166:169], v[58:61]
	v_mfma_f32_16x16x32_bf16 v[34:37], v[214:217], v[170:173], v[34:37]
	v_mfma_f32_16x16x32_bf16 v[18:21], v[214:217], v[174:177], v[18:21]
	v_mfma_f32_16x16x32_bf16 v[2:5], v[214:217], v[178:181], v[2:5]
	s_waitcnt vmcnt(0)
	s_lshl_b32 s22, s24, 19
	v_readlane_b32 s23, v255, 33
	v_readlane_b32 s4, v255, 26
	s_nop 0
	s_add_i32 s13, s13, s23
	v_readlane_b32 s23, v255, 30
	s_nop 0
	s_add_i32 s12, s12, s23
	v_readlane_b32 s23, v255, 34
	s_nop 0
	s_add_i32 s11, s11, s23
	v_readlane_b32 s5, v255, 27
	v_and_b32_e32 v0, 15, v188
	v_lshrrev_b32_e32 v164, 1, v188
	v_and_or_b32 v0, v164, 64, v0
	v_lshl_or_b32 v0, v0, 12, s22
	v_lshrrev_b32_e32 v164, 2, v188
	v_and_b32_e32 v164, 12, v164
	v_lshlrev_b32_e32 v165, 1, v188
	v_and_b32_e32 v165, 0x80, v165
	v_or3_b32 v164, v164, v165, s25
	v_lshlrev_b32_e32 v164, 2, v164
	v_add_u32_e32 v0, v0, v164
	s_lshr_b32 s22, s4, 3
	s_add_i32 s7, s7, s22
	v_mov_b32_e32 v164, 0
	v_mov_b32_e32 v178, v0
	v_mov_b32_e32 v179, 0
	v_lshl_add_u64 v[180:181], s[56:57], 0, v[178:179]
	v_lshl_add_u64 v[178:179], s[0:1], 0, v[178:179]
	s_mov_b64 s[28:29], 0x10000
	v_lshl_add_u64 v[182:183], v[178:179], 0, s[28:29]
	v_lshl_add_u64 v[184:185], v[180:181], 0, s[28:29]
	v_lshl_add_u64 v[186:187], v[182:183], 0, s[28:29]
	v_lshl_add_u64 v[158:159], v[184:185], 0, s[28:29]
	v_lshl_add_u64 v[160:161], v[186:187], 0, s[28:29]
	v_lshl_add_u64 v[162:163], v[158:159], 0, s[28:29]
	global_load_dwordx4 v[90:93], v[178:179], off offset:0
	global_load_dwordx4 v[94:97], v[178:179], off offset:64
	global_load_dwordx4 v[106:109], v[178:179], off offset:128
	global_load_dwordx4 v[110:113], v[178:179], off offset:192
	global_load_dwordx4 v[114:117], v[178:179], off offset:256
	global_load_dwordx4 v[118:121], v[178:179], off offset:320
	global_load_dwordx4 v[154:157], v[178:179], off offset:384
	global_load_dwordx4 v[166:169], v[178:179], off offset:448
	global_load_dwordx4 v[170:173], v[182:183], off offset:0
	global_load_dwordx4 v[174:177], v[182:183], off offset:64
	global_load_dwordx4 v[190:193], v[182:183], off offset:128
	global_load_dwordx4 v[194:197], v[182:183], off offset:192
	s_waitcnt vmcnt(11)
; DI int otid() { int t; asm volatile("v_mov_b32 %0, %1" : "=v"(t) : "v"((int)threadIdx.x)); __builtin_assume(t >= 0 && t < 256); return t; }
; DI void outproj_tile(const Params& p, int l, int tile, char* smem) {
;     ...
;   const float* xin = l == 0 ? p.x : p.out;
;   const int lane = otid() & 63, wid = otid() >> 6, wm = wid >> 1, wn = wid & 1, fr = lane & 15, fq = lane >> 4;
; #pragma unroll
;   for (int mi = 0; mi < 4; ++mi)
; #pragma unroll
;     for (int ni = 0; ni < 8; ++ni) {
;       size_t row = (size_t)mt * 128 + wm * 64 + mi * 16 + fr; int col = nt * 256 + wn * 128 + ni * 16 + fq * 4;
;       float4 xi = *(const float4*)(xin + row * 1024 + col);
;       float4 o; o.x = xi.x + acc[mi][ni][0]; o.y = xi.y + acc[mi][ni][1]; o.z = xi.z + acc[mi][ni][2]; o.w = xi.w + acc[mi][ni][3];
;       *(float4*)(p.out + row * 1024 + col) = o;
;     }
	v_add_f32_e32 v150, v150, v90
	v_add_f32_e32 v151, v151, v91
	v_add_f32_e32 v152, v152, v92
	v_add_f32_e32 v153, v153, v93
	global_store_dwordx4 v[180:181], v[150:153], off offset:0
	global_load_dwordx4 v[90:93], v[182:183], off offset:256
	s_waitcnt vmcnt(12)
	v_add_f32_e32 v146, v146, v94
	v_add_f32_e32 v147, v147, v95
	v_add_f32_e32 v148, v148, v96
	v_add_f32_e32 v149, v149, v97
	global_store_dwordx4 v[180:181], v[146:149], off offset:64
	global_load_dwordx4 v[94:97], v[182:183], off offset:320
	s_waitcnt vmcnt(13)
	v_add_f32_e32 v142, v142, v106
	v_add_f32_e32 v143, v143, v107
	v_add_f32_e32 v144, v144, v108
	v_add_f32_e32 v145, v145, v109
	global_store_dwordx4 v[180:181], v[142:145], off offset:128
	global_load_dwordx4 v[106:109], v[182:183], off offset:384
	s_waitcnt vmcnt(14)
	v_add_f32_e32 v138, v138, v110
	v_add_f32_e32 v139, v139, v111
	v_add_f32_e32 v140, v140, v112
	v_add_f32_e32 v141, v141, v113
	global_store_dwordx4 v[180:181], v[138:141], off offset:192
	global_load_dwordx4 v[110:113], v[182:183], off offset:448
	s_waitcnt vmcnt(15)
	v_add_f32_e32 v102, v102, v114
	v_add_f32_e32 v103, v103, v115
	v_add_f32_e32 v104, v104, v116
	v_add_f32_e32 v105, v105, v117
	global_store_dwordx4 v[180:181], v[102:105], off offset:256
	global_load_dwordx4 v[114:117], v[186:187], off offset:0
	s_waitcnt vmcnt(16)
	v_add_f32_e32 v82, v82, v118
	v_add_f32_e32 v83, v83, v119
	v_add_f32_e32 v84, v84, v120
	v_add_f32_e32 v85, v85, v121
	global_store_dwordx4 v[180:181], v[82:85], off offset:320
	global_load_dwordx4 v[118:121], v[186:187], off offset:64
	s_waitcnt vmcnt(17)
	v_add_f32_e32 v70, v70, v154
	v_add_f32_e32 v71, v71, v155
	v_add_f32_e32 v72, v72, v156
	v_add_f32_e32 v73, v73, v157
	global_store_dwordx4 v[180:181], v[70:73], off offset:384
	global_load_dwordx4 v[154:157], v[186:187], off offset:128
	s_waitcnt vmcnt(18)
	v_add_f32_e32 v58, v58, v166
	v_add_f32_e32 v59, v59, v167
	v_add_f32_e32 v60, v60, v168
	v_add_f32_e32 v61, v61, v169
	global_store_dwordx4 v[180:181], v[58:61], off offset:448
	global_load_dwordx4 v[166:169], v[186:187], off offset:192
	s_waitcnt vmcnt(19)
	v_add_f32_e32 v134, v134, v170
	v_add_f32_e32 v135, v135, v171
	v_add_f32_e32 v136, v136, v172
	v_add_f32_e32 v137, v137, v173
	global_store_dwordx4 v[184:185], v[134:137], off offset:0
	global_load_dwordx4 v[170:173], v[186:187], off offset:256
	s_waitcnt vmcnt(20)
	v_add_f32_e32 v130, v130, v174
	v_add_f32_e32 v131, v131, v175
	v_add_f32_e32 v132, v132, v176
	v_add_f32_e32 v133, v133, v177
	global_store_dwordx4 v[184:185], v[130:133], off offset:64
	global_load_dwordx4 v[174:177], v[186:187], off offset:320
	s_waitcnt vmcnt(21)
	v_add_f32_e32 v126, v126, v190
	v_add_f32_e32 v127, v127, v191
	v_add_f32_e32 v128, v128, v192
	v_add_f32_e32 v129, v129, v193
	global_store_dwordx4 v[184:185], v[126:129], off offset:128
	global_load_dwordx4 v[190:193], v[186:187], off offset:384
	s_waitcnt vmcnt(22)
	v_add_f32_e32 v122, v122, v194
	v_add_f32_e32 v123, v123, v195
	v_add_f32_e32 v124, v124, v196
	v_add_f32_e32 v125, v125, v197
	global_store_dwordx4 v[184:185], v[122:125], off offset:192
	global_load_dwordx4 v[194:197], v[186:187], off offset:448
	s_waitcnt vmcnt(22)
	v_add_f32_e32 v46, v46, v90
	v_add_f32_e32 v47, v47, v91
	v_add_f32_e32 v48, v48, v92
	v_add_f32_e32 v49, v49, v93
	global_store_dwordx4 v[184:185], v[46:49], off offset:256
	global_load_dwordx4 v[90:93], v[160:161], off offset:0
	s_waitcnt vmcnt(22)
	v_add_f32_e32 v42, v42, v94
	v_add_f32_e32 v43, v43, v95
	v_add_f32_e32 v44, v44, v96
	v_add_f32_e32 v45, v45, v97
	global_store_dwordx4 v[184:185], v[42:45], off offset:320
	global_load_dwordx4 v[94:97], v[160:161], off offset:64
	s_waitcnt vmcnt(22)
	v_add_f32_e32 v38, v38, v106
	v_add_f32_e32 v39, v39, v107
	v_add_f32_e32 v40, v40, v108
	v_add_f32_e32 v41, v41, v109
	global_store_dwordx4 v[184:185], v[38:41], off offset:384
	global_load_dwordx4 v[106:109], v[160:161], off offset:128
	s_waitcnt vmcnt(22)
; DI int otid() { int t; asm volatile("v_mov_b32 %0, %1" : "=v"(t) : "v"((int)threadIdx.x)); __builtin_assume(t >= 0 && t < 256); return t; }
; DI void outproj_tile(const Params& p, int l, int tile, char* smem) {
;     ...
;   const float* xin = l == 0 ? p.x : p.out;
;   const int lane = otid() & 63, wid = otid() >> 6, wm = wid >> 1, wn = wid & 1, fr = lane & 15, fq = lane >> 4;
; #pragma unroll
;   for (int mi = 0; mi < 4; ++mi)
; #pragma unroll
;     for (int ni = 0; ni < 8; ++ni) {
;       size_t row = (size_t)mt * 128 + wm * 64 + mi * 16 + fr; int col = nt * 256 + wn * 128 + ni * 16 + fq * 4;
;       float4 xi = *(const float4*)(xin + row * 1024 + col);
;       float4 o; o.x = xi.x + acc[mi][ni][0]; o.y = xi.y + acc[mi][ni][1]; o.z = xi.z + acc[mi][ni][2]; o.w = xi.w + acc[mi][ni][3];
;       *(float4*)(p.out + row * 1024 + col) = o;
;     }
	v_add_f32_e32 v34, v34, v110
	v_add_f32_e32 v35, v35, v111
	v_add_f32_e32 v36, v36, v112
	v_add_f32_e32 v37, v37, v113
	global_store_dwordx4 v[184:185], v[34:37], off offset:448
	global_load_dwordx4 v[110:113], v[160:161], off offset:192
	s_waitcnt vmcnt(22)
	v_add_f32_e32 v98, v98, v114
	v_add_f32_e32 v99, v99, v115
	v_add_f32_e32 v100, v100, v116
	v_add_f32_e32 v101, v101, v117
	global_store_dwordx4 v[158:159], v[98:101], off offset:0
	global_load_dwordx4 v[114:117], v[160:161], off offset:256
	s_waitcnt vmcnt(22)
	v_add_f32_e32 v86, v86, v118
	v_add_f32_e32 v87, v87, v119
	v_add_f32_e32 v88, v88, v120
	v_add_f32_e32 v89, v89, v121
	global_store_dwordx4 v[158:159], v[86:89], off offset:64
	global_load_dwordx4 v[118:121], v[160:161], off offset:320
	s_waitcnt vmcnt(22)
	v_add_f32_e32 v78, v78, v154
	v_add_f32_e32 v79, v79, v155
	v_add_f32_e32 v80, v80, v156
	v_add_f32_e32 v81, v81, v157
	global_store_dwordx4 v[158:159], v[78:81], off offset:128
	global_load_dwordx4 v[154:157], v[160:161], off offset:384
	s_waitcnt vmcnt(22)
	v_add_f32_e32 v74, v74, v166
	v_add_f32_e32 v75, v75, v167
	v_add_f32_e32 v76, v76, v168
	v_add_f32_e32 v77, v77, v169
	global_store_dwordx4 v[158:159], v[74:77], off offset:192
	global_load_dwordx4 v[166:169], v[160:161], off offset:448
	s_waitcnt vmcnt(22)
	v_add_f32_e32 v30, v30, v170
	v_add_f32_e32 v31, v31, v171
	v_add_f32_e32 v32, v32, v172
	v_add_f32_e32 v33, v33, v173
	global_store_dwordx4 v[158:159], v[30:33], off offset:256
	s_waitcnt vmcnt(21)
	v_add_f32_e32 v26, v26, v174
	v_add_f32_e32 v27, v27, v175
	v_add_f32_e32 v28, v28, v176
	v_add_f32_e32 v29, v29, v177
	global_store_dwordx4 v[158:159], v[26:29], off offset:320
	s_waitcnt vmcnt(20)
	v_add_f32_e32 v22, v22, v190
	v_add_f32_e32 v23, v23, v191
	v_add_f32_e32 v24, v24, v192
	v_add_f32_e32 v25, v25, v193
	global_store_dwordx4 v[158:159], v[22:25], off offset:384
	s_waitcnt vmcnt(19)
	v_add_f32_e32 v18, v18, v194
	v_add_f32_e32 v19, v19, v195
	v_add_f32_e32 v20, v20, v196
	v_add_f32_e32 v21, v21, v197
	global_store_dwordx4 v[158:159], v[18:21], off offset:448
	s_waitcnt vmcnt(18)
	v_add_f32_e32 v66, v66, v90
	v_add_f32_e32 v67, v67, v91
	v_add_f32_e32 v68, v68, v92
	v_add_f32_e32 v69, v69, v93
	global_store_dwordx4 v[162:163], v[66:69], off offset:0
	s_waitcnt vmcnt(17)
	v_add_f32_e32 v62, v62, v94
	v_add_f32_e32 v63, v63, v95
	v_add_f32_e32 v64, v64, v96
	v_add_f32_e32 v65, v65, v97
	global_store_dwordx4 v[162:163], v[62:65], off offset:64
	s_waitcnt vmcnt(16)
	v_add_f32_e32 v54, v54, v106
	v_add_f32_e32 v55, v55, v107
	v_add_f32_e32 v56, v56, v108
	v_add_f32_e32 v57, v57, v109
	global_store_dwordx4 v[162:163], v[54:57], off offset:128
	s_waitcnt vmcnt(15)
	v_add_f32_e32 v50, v50, v110
	v_add_f32_e32 v51, v51, v111
	v_add_f32_e32 v52, v52, v112
	v_add_f32_e32 v53, v53, v113
	global_store_dwordx4 v[162:163], v[50:53], off offset:192
	s_waitcnt vmcnt(14)
	v_add_f32_e32 v14, v14, v114
	v_add_f32_e32 v15, v15, v115
	v_add_f32_e32 v16, v16, v116
	v_add_f32_e32 v17, v17, v117
	global_store_dwordx4 v[162:163], v[14:17], off offset:256
	s_waitcnt vmcnt(13)
	v_add_f32_e32 v10, v10, v118
	v_add_f32_e32 v11, v11, v119
	v_add_f32_e32 v12, v12, v120
	v_add_f32_e32 v13, v13, v121
	global_store_dwordx4 v[162:163], v[10:13], off offset:320
	s_waitcnt vmcnt(12)
	v_add_f32_e32 v6, v6, v154
	v_add_f32_e32 v7, v7, v155
	v_add_f32_e32 v8, v8, v156
	v_add_f32_e32 v9, v9, v157
	global_store_dwordx4 v[162:163], v[6:9], off offset:384
	s_waitcnt vmcnt(11)
	v_add_f32_e32 v2, v2, v166
	v_add_f32_e32 v3, v3, v167
	v_add_f32_e32 v4, v4, v168
	v_add_f32_e32 v5, v5, v169
	global_store_dwordx4 v[162:163], v[2:5], off offset:448
	s_cmpk_gt_i32 s13, 0x7f
	s_cbranch_scc0 .LBB0_237
